# out-proj and residual+final-norm fused per row panel (panel counters, 2-class schedule), P5 phase skipped
# speedup vs baseline: 1.1177x; 1.0125x over previous
.LBB0_320:
	s_mov_b32 s78, 0
	s_cmp_lg_u32 s74, 0
	s_cbranch_scc1 .Lxt_skip
	s_getreg_b32 s76, hwreg(HW_REG_XCC_ID, 0, 4)
	s_lshl_b32 s76, 1, s76
	s_lshr_b32 s77, s75, 5
	s_lshl_b32 s77, s77, 2
	s_add_u32 s82, s42, 0x60d3c00
	s_addc_u32 s83, s43, 0
	v_mov_b32_e32 v20, s77
	v_mov_b32_e32 v21, s76
	s_mov_b64 s[80:81], exec
	s_mov_b64 exec, 1
	global_atomic_or v20, v21, s[82:83] sc1
	s_mov_b64 exec, s[80:81]

.LBB0_372:
	s_or_b64 exec, exec, s[2:3]
	s_cmpk_gt_i32 s75, 0x2ff
	s_waitcnt lgkmcnt(0)
	s_barrier
	s_cbranch_scc1 .LBB0_377
	s_mov_b32 s78, 0
	v_readlane_b32 s64, v254, 9
	s_cmpk_lg_i32 s64, 0x100
	s_cbranch_scc1 .Lp45_nofuse
	s_add_u32 s66, s42, 0x60d3c00
	s_addc_u32 s67, s43, 0
	v_mov_b32_e32 v20, 0
	global_load_dwordx4 v[24:27], v20, s[66:67] sc1
	global_load_dwordx4 v[28:31], v20, s[66:67] offset:16 sc1
	s_waitcnt vmcnt(0)
	v_readfirstlane_b32 s64, v24
	s_bcnt1_i32_b32 s64, s64
	s_cmp_lg_u32 s64, 1
	s_cbranch_scc1 .Lp45_nofuse
	v_readfirstlane_b32 s64, v25
	s_bcnt1_i32_b32 s64, s64
	s_cmp_lg_u32 s64, 1
	s_cbranch_scc1 .Lp45_nofuse
	v_readfirstlane_b32 s64, v26
	s_bcnt1_i32_b32 s64, s64
	s_cmp_lg_u32 s64, 1
	s_cbranch_scc1 .Lp45_nofuse
	v_readfirstlane_b32 s64, v27
	s_bcnt1_i32_b32 s64, s64
	s_cmp_lg_u32 s64, 1
	s_cbranch_scc1 .Lp45_nofuse
	v_readfirstlane_b32 s64, v28
	s_bcnt1_i32_b32 s64, s64
	s_cmp_lg_u32 s64, 1
	s_cbranch_scc1 .Lp45_nofuse
	v_readfirstlane_b32 s64, v29
	s_bcnt1_i32_b32 s64, s64
	s_cmp_lg_u32 s64, 1
	s_cbranch_scc1 .Lp45_nofuse
	v_readfirstlane_b32 s64, v30
	s_bcnt1_i32_b32 s64, s64
	s_cmp_lg_u32 s64, 1
	s_cbranch_scc1 .Lp45_nofuse
	v_readfirstlane_b32 s64, v31
	s_bcnt1_i32_b32 s64, s64
	s_cmp_lg_u32 s64, 1
	s_cbranch_scc1 .Lp45_nofuse
	s_mov_b32 s78, 1
	s_add_u32 s80, s42, 0x60d3800
	s_addc_u32 s81, s43, 0
	s_bfe_u32 s79, s75, 0x10002
	s_mov_b32 s82, 0
	s_mov_b32 s83, 0
	s_mov_b32 s84, s75
.Lp45_nofuse:
	v_readlane_b32 s2, v254, 26
	v_lshlrev_b32_e32 v2, 9, v189
	v_readlane_b32 s4, v254, 28
	v_bitop3_b32 v1, v197, v215, 3 bitop3:0x78
	s_lshl_b32 s2, s2, 5
	v_lshl_or_b32 v2, s4, 15, v2
	v_lshlrev_b32_e32 v140, 4, v1
	v_or_b32_e32 v1, s2, v197
	v_add_u32_e32 v6, 0, v2
	v_bitop3_b32 v2, s2, v189, v197 bitop3:0x36
	v_lshlrev_b32_e32 v7, 3, v2
	v_bitop3_b32 v2, v1, v189, 2 bitop3:0x36
	v_lshlrev_b32_e32 v8, 3, v2
	v_bitop3_b32 v2, v1, v189, 4 bitop3:0x36
	v_lshlrev_b32_e32 v9, 3, v2
	v_bitop3_b32 v2, v1, v189, 6 bitop3:0x36
	v_lshlrev_b32_e32 v10, 3, v2
	v_bitop3_b32 v2, v1, v189, 8 bitop3:0x36
	v_lshlrev_b32_e32 v11, 3, v2
	v_bitop3_b32 v2, v1, v189, 10 bitop3:0x36
	v_lshlrev_b32_e32 v12, 3, v2
	v_bitop3_b32 v2, v1, v189, 12 bitop3:0x36
	v_lshlrev_b32_e32 v13, 3, v2
	v_bitop3_b32 v2, v1, v189, 14 bitop3:0x36
	v_lshlrev_b32_e32 v14, 3, v2
	v_bitop3_b32 v2, v1, v189, 16 bitop3:0x36
	v_lshlrev_b32_e32 v15, 3, v2
	v_bitop3_b32 v2, v1, v189, 18 bitop3:0x36
	v_lshlrev_b32_e32 v16, 3, v2
	v_bitop3_b32 v2, v1, v189, 20 bitop3:0x36
	v_lshlrev_b32_e32 v17, 3, v2
	v_bitop3_b32 v2, v1, v189, 22 bitop3:0x36
	v_lshlrev_b32_e32 v18, 3, v2
	v_bitop3_b32 v2, v1, v189, 24 bitop3:0x36
	v_lshlrev_b32_e32 v19, 3, v2
	v_bitop3_b32 v2, v1, v189, 26 bitop3:0x36
	v_lshlrev_b32_e32 v20, 3, v2
	v_bitop3_b32 v2, v1, v189, 28 bitop3:0x36
	v_lshlrev_b32_e32 v21, 3, v2
	v_bitop3_b32 v2, v1, v189, 30 bitop3:0x36
	v_lshlrev_b32_e32 v22, 3, v2
	v_bitop3_b32 v2, s2, v213, v197 bitop3:0x36
	v_lshlrev_b32_e32 v23, 3, v2
	v_bitop3_b32 v2, v1, v213, 2 bitop3:0x36
	v_lshlrev_b32_e32 v24, 3, v2
	v_bitop3_b32 v2, v1, v213, 4 bitop3:0x36
	v_lshlrev_b32_e32 v25, 3, v2
	v_bitop3_b32 v2, v1, v213, 6 bitop3:0x36
	v_lshlrev_b32_e32 v26, 3, v2
	v_bitop3_b32 v2, v1, v213, 8 bitop3:0x36
	v_lshlrev_b32_e32 v27, 3, v2
	v_bitop3_b32 v2, v1, v213, 10 bitop3:0x36
	v_lshlrev_b32_e32 v28, 3, v2
	v_bitop3_b32 v2, v1, v213, 12 bitop3:0x36
	v_lshlrev_b32_e32 v29, 3, v2
	v_bitop3_b32 v2, v1, v213, 14 bitop3:0x36
	v_lshlrev_b32_e32 v30, 3, v2
	v_bitop3_b32 v2, v1, v213, 16 bitop3:0x36
	v_lshlrev_b32_e32 v31, 3, v2
	v_bitop3_b32 v2, v1, v213, 18 bitop3:0x36
	v_lshlrev_b32_e32 v32, 3, v2
	v_bitop3_b32 v2, v1, v213, 20 bitop3:0x36
	v_lshlrev_b32_e32 v33, 3, v2
	v_bitop3_b32 v2, v1, v213, 22 bitop3:0x36
	v_lshlrev_b32_e32 v34, 3, v2
	v_bitop3_b32 v2, v1, v213, 24 bitop3:0x36
	v_lshlrev_b32_e32 v35, 3, v2
	v_bitop3_b32 v2, v1, v213, 26 bitop3:0x36
	s_lshl_b32 s3, s74, 1
	v_lshlrev_b32_e32 v36, 3, v2
	v_bitop3_b32 v2, v1, v213, 28 bitop3:0x36
	v_mov_b32_e32 v129, 0
	v_lshlrev_b32_e32 v37, 3, v2
	v_or_b32_e32 v2, s3, v197
	v_add_u32_e32 v128, 16, v2
	v_mov_b32_e32 v3, v129
	v_xor_b32_e32 v0, v216, v191
	v_lshlrev_b64 v[4:5], 11, v[128:129]
	v_and_b32_e32 v38, 0x1f0, v212
	v_lshlrev_b64 v[2:3], 11, v[2:3]
	v_lshlrev_b32_e32 v0, 3, v0
	v_bitop3_b32 v1, v1, v213, 30 bitop3:0x36
	s_add_i32 s2, s3, 16
	v_or_b32_e32 v4, v4, v38
	s_lshl_b32 s4, s74, 10
	v_or_b32_e32 v2, v2, v38
	v_and_b32_e32 v0, 24, v0
	v_lshlrev_b32_e32 v1, 3, v1
	s_lshr_b32 s11, s2, 1
	v_lshl_add_u64 v[4:5], s[42:43], 0, v[4:5]
	s_mov_b64 s[2:3], 0xb800000
	s_add_i32 s4, s4, 0
	v_lshl_add_u64 v[2:3], s[42:43], 0, v[2:3]
	v_lshlrev_b32_e32 v141, 4, v214
	v_cmp_gt_u32_e32 vcc, 32, v190
	v_lshl_add_u64 v[130:131], v[4:5], 0, s[2:3]
	v_lshl_add_u32 v148, v197, 9, s4
	v_lshl_add_u64 v[132:133], v[2:3], 0, s[2:3]
	v_lshlrev_b32_e32 v134, 1, v0
	v_mov_b32_e32 v135, v129
	s_mov_b64 s[88:89], 0x40440
	s_mov_b64 s[90:91], 0x480
	s_mov_b64 s[92:93], 0x40480
	s_mov_b64 s[94:95], 0x4c0
	s_mov_b64 s[96:97], 0x404c0
	s_mov_b64 s[98:99], 0x500
	s_mov_b64 s[46:47], 0x40500
	s_mov_b64 s[28:29], 0x540
	v_add_u32_e32 v149, v6, v7
	v_add_u32_e32 v150, v6, v8
	v_add_u32_e32 v151, v6, v9
	v_add_u32_e32 v152, v6, v10
	v_add_u32_e32 v153, v6, v11
	v_add_u32_e32 v154, v6, v12
	v_add_u32_e32 v155, v6, v13
	v_add_u32_e32 v156, v6, v14
	v_add_u32_e32 v157, v6, v15
	v_add_u32_e32 v158, v6, v16
	v_add_u32_e32 v159, v6, v17
	v_add_u32_e32 v160, v6, v18
	v_add_u32_e32 v161, v6, v19
	v_add_u32_e32 v162, v6, v20
	v_add_u32_e32 v163, v6, v21
	v_add_u32_e32 v164, v6, v22
	v_add_u32_e32 v165, v6, v23
	v_add_u32_e32 v166, v6, v24
	v_add_u32_e32 v167, v6, v25
	v_add_u32_e32 v168, v6, v26
	v_add_u32_e32 v169, v6, v27
	v_add_u32_e32 v170, v6, v28
	v_add_u32_e32 v171, v6, v29
	v_add_u32_e32 v172, v6, v30
	v_add_u32_e32 v173, v6, v31
	v_add_u32_e32 v174, v6, v32
	v_add_u32_e32 v175, v6, v33
	v_add_u32_e32 v176, v6, v34
	v_add_u32_e32 v177, v6, v35
	v_add_u32_e32 v178, v6, v36
	v_add_u32_e32 v179, v6, v37
	v_add_u32_e32 v180, v6, v1
	s_mov_b32 s33, s75
	s_mov_b64 s[44:45], 0x40540
	s_mov_b64 s[2:3], 0x580
	s_mov_b64 s[4:5], 0x40580
	s_mov_b64 s[6:7], 0x5c0
	s_mov_b64 s[8:9], 0x405c0
	s_mov_b64 s[16:17], 0x600
	s_mov_b64 s[18:19], 0x40600
	s_mov_b64 s[20:21], 0x640
	s_mov_b64 s[22:23], 0x40640
	s_mov_b64 s[24:25], 0x680
	s_mov_b64 s[26:27], 0x40680
	s_mov_b64 s[30:31], 0x6c0
	s_mov_b64 s[34:35], 0x406c0
	s_mov_b64 s[36:37], 0x700
	s_mov_b64 s[48:49], 0x40700
	s_mov_b64 s[50:51], 0x740
	s_mov_b64 s[52:53], 0x40740
	s_mov_b64 s[54:55], 0x780
	s_mov_b64 s[56:57], 0x40780
	s_mov_b64 s[58:59], 0x7c0
	s_mov_b64 s[60:61], 0x407c0
	s_mov_b64 s[62:63], 0x10000

.LBB0_375:
	s_add_i32 s65, s74, s64
	v_xor_b32_e32 v5, s65, v191
	v_lshlrev_b32_e32 v5, 4, v5
	v_and_b32_e32 v5, 0x1f0, v5
	v_add_u32_e32 v5, v4, v5
	ds_read_b128 v[6:9], v5
	s_add_i32 s65, s11, s64
	v_xor_b32_e32 v5, s65, v191
	v_lshlrev_b32_e32 v5, 4, v5
	v_and_b32_e32 v5, 0x1f0, v5
	s_waitcnt lgkmcnt(0)
	v_cndmask_b32_e32 v11, v7, v9, vcc
	v_cndmask_b32_e32 v10, v6, v8, vcc
	v_cndmask_b32_e32 v9, v9, v7, vcc
	v_cndmask_b32_e32 v8, v8, v6, vcc
	v_add_u32_e32 v5, v4, v5
	global_store_dwordx4 v[2:3], v[8:11], off
	ds_read_b128 v[6:9], v5 offset:8192
	s_add_i32 s64, s64, 16
	v_add_u32_e32 v4, 0x4000, v4
	v_lshl_add_u64 v[2:3], v[2:3], 0, s[62:63]
	s_cmpk_lg_i32 s64, 0x80
	s_waitcnt lgkmcnt(0)
	v_cndmask_b32_e32 v11, v7, v9, vcc
	v_cndmask_b32_e32 v10, v6, v8, vcc
	v_cndmask_b32_e32 v9, v9, v7, vcc
	v_cndmask_b32_e32 v8, v8, v6, vcc
	global_store_dwordx4 v[0:1], v[8:11], off
	v_lshl_add_u64 v[0:1], v[0:1], 0, s[62:63]
	s_cbranch_scc1 .LBB0_375
	s_cmp_eq_u32 s78, 0
	s_cbranch_scc1 .Lp45_skip
	s_waitcnt vmcnt(0)
	s_barrier
	s_cmp_lg_u32 s74, 0
	s_cbranch_scc1 .Lp45_posted
	s_lshr_b32 s64, s75, 2
	s_lshl_b32 s64, s64, 2
	v_mov_b32_e32 v122, s64
	v_mov_b32_e32 v123, 1
	s_mov_b64 s[66:67], exec
	s_mov_b64 exec, 1
	global_atomic_add v122, v123, s[80:81] sc1
	s_mov_b64 exec, s[66:67]
.Lp45_posted:
	s_add_i32 s82, s82, 1
	s_mov_b32 s86, s82
	s_cmp_eq_u32 s79, 0
	s_cbranch_scc1 .Lp45_loop
	s_add_i32 s86, s82, -1
	s_cmp_eq_u32 s82, 3
	s_cselect_b32 s86, 3, s86
.Lp45_loop:
	s_cmp_ge_u32 s83, s86
	s_cbranch_scc1 .Lp45_skip
	s_lshr_b32 s64, s84, 2
	s_lshl_b32 s65, s83, 6
	s_add_i32 s64, s64, s65
	s_cmp_lg_u32 s74, 0
	s_cbranch_scc1 .Lp45_ready
	s_lshl_b32 s65, s64, 2
	v_mov_b32_e32 v122, s65
	s_mov_b32 s67, 0
.Lp45_spin:
	global_load_dword v123, v122, s[80:81] sc1
	s_waitcnt vmcnt(0)
	v_readfirstlane_b32 s66, v123
	s_cmp_ge_u32 s66, 4
	s_cbranch_scc1 .Lp45_ready
	s_sleep 1
	s_add_i32 s67, s67, 1
	s_cmp_lt_u32 s67, 0x8000
	s_cbranch_scc1 .Lp45_spin
.Lp45_ready:
	s_barrier
	s_lshl_b32 s66, s64, 8
	s_and_b32 s67, s84, 3
	s_lshl_b32 s67, s67, 6
	s_add_i32 s66, s66, s67
	s_lshl_b32 s67, s74, 3
	s_add_i32 s66, s66, s67
	s_cmp_lt_u32 s66, 0x8000
	s_cselect_b32 s52, s12, s14
	s_cselect_b32 s53, s13, s15
	s_cselect_b32 s67, 0, 0x8000
	s_sub_u32 s67, s66, s67
	s_lshl_b32 s67, s67, 12
	s_add_u32 s52, s52, s67
	s_addc_u32 s53, s53, 0
	v_readlane_b32 s54, v254, 22
	v_readlane_b32 s55, v254, 23
	s_lshl_b32 s67, s66, 11
	s_add_u32 s54, s54, s67
	s_addc_u32 s55, s55, 0
	s_lshl_b32 s67, s66, 12
	s_add_u32 s56, s40, s67
	s_addc_u32 s57, s41, 0
	v_mov_b32_e32 v124, 0x358637bd
	global_load_dwordx4 v[196:199], v194, s[38:39] offset:0
	global_load_dwordx4 v[200:203], v194, s[38:39] offset:1024
	global_load_dwordx4 v[204:207], v194, s[38:39] offset:2048
	global_load_dwordx4 v[208:211], v194, s[38:39] offset:3072
	s_mov_b64 s[2:3], s[52:53]
	s_mov_b64 s[44:45], s[56:57]
	s_mov_b64 s[26:27], s[54:55]
	global_load_dwordx2 v[82:83], v188, s[26:27] offset:0 sc1
	global_load_dwordx2 v[84:85], v188, s[26:27] offset:512 sc1
	global_load_dwordx2 v[86:87], v188, s[26:27] offset:1024 sc1
	global_load_dwordx2 v[88:89], v188, s[26:27] offset:1536 sc1
	global_load_dwordx4 v[18:21], v194, s[2:3] offset:0 nt
	global_load_dwordx4 v[22:25], v194, s[2:3] offset:1024 nt
	global_load_dwordx4 v[26:29], v194, s[2:3] offset:2048 nt
	global_load_dwordx4 v[30:33], v194, s[2:3] offset:3072 nt
	s_add_u32 s4, s52, 0x1000
	s_addc_u32 s5, s53, 0
	s_add_u32 s46, s56, 0x1000
	s_addc_u32 s47, s57, 0
	s_add_u32 s28, s54, 0x800
	s_addc_u32 s29, s55, 0
	global_load_dwordx2 v[90:91], v188, s[28:29] offset:0 sc1
	global_load_dwordx2 v[92:93], v188, s[28:29] offset:512 sc1
	global_load_dwordx2 v[94:95], v188, s[28:29] offset:1024 sc1
	global_load_dwordx2 v[96:97], v188, s[28:29] offset:1536 sc1
	global_load_dwordx4 v[34:37], v194, s[4:5] offset:0 nt
	global_load_dwordx4 v[38:41], v194, s[4:5] offset:1024 nt
	global_load_dwordx4 v[42:45], v194, s[4:5] offset:2048 nt
	global_load_dwordx4 v[46:49], v194, s[4:5] offset:3072 nt
	s_add_u32 s6, s52, 0x2000
	s_addc_u32 s7, s53, 0
	s_add_u32 s48, s56, 0x2000
	s_addc_u32 s49, s57, 0
	s_add_u32 s30, s54, 0x1000
	s_addc_u32 s31, s55, 0
	global_load_dwordx2 v[98:99], v188, s[30:31] offset:0 sc1
	global_load_dwordx2 v[100:101], v188, s[30:31] offset:512 sc1
	global_load_dwordx2 v[102:103], v188, s[30:31] offset:1024 sc1
	global_load_dwordx2 v[104:105], v188, s[30:31] offset:1536 sc1
	global_load_dwordx4 v[50:53], v194, s[6:7] offset:0 nt
	global_load_dwordx4 v[54:57], v194, s[6:7] offset:1024 nt
	global_load_dwordx4 v[58:61], v194, s[6:7] offset:2048 nt
	global_load_dwordx4 v[62:65], v194, s[6:7] offset:3072 nt
	s_add_u32 s8, s52, 0x3000
	s_addc_u32 s9, s53, 0
	s_add_u32 s50, s56, 0x3000
	s_addc_u32 s51, s57, 0
	s_add_u32 s34, s54, 0x1800
	s_addc_u32 s35, s55, 0
	global_load_dwordx2 v[106:107], v188, s[34:35] offset:0 sc1
	global_load_dwordx2 v[108:109], v188, s[34:35] offset:512 sc1
	global_load_dwordx2 v[110:111], v188, s[34:35] offset:1024 sc1
	global_load_dwordx2 v[112:113], v188, s[34:35] offset:1536 sc1
	global_load_dwordx4 v[66:69], v194, s[8:9] offset:0 nt
	global_load_dwordx4 v[70:73], v194, s[8:9] offset:1024 nt
	global_load_dwordx4 v[74:77], v194, s[8:9] offset:2048 nt
	global_load_dwordx4 v[78:81], v194, s[8:9] offset:3072 nt
	s_waitcnt vmcnt(24)
	v_lshlrev_b32_e32 v118, 16, v82
	v_and_b32_e32 v119, 0xffff0000, v82
	v_lshlrev_b32_e32 v120, 16, v83
	v_and_b32_e32 v121, 0xffff0000, v83
	v_add_f32_e32 v18, v18, v118
	v_add_f32_e32 v19, v19, v119
	v_add_f32_e32 v20, v20, v120
	v_add_f32_e32 v21, v21, v121
	v_lshlrev_b32_e32 v118, 16, v84
	v_and_b32_e32 v119, 0xffff0000, v84
	v_lshlrev_b32_e32 v120, 16, v85
	v_and_b32_e32 v121, 0xffff0000, v85
	v_add_f32_e32 v22, v22, v118
	v_add_f32_e32 v23, v23, v119
	v_add_f32_e32 v24, v24, v120
	v_add_f32_e32 v25, v25, v121
	v_lshlrev_b32_e32 v118, 16, v86
	v_and_b32_e32 v119, 0xffff0000, v86
	v_lshlrev_b32_e32 v120, 16, v87
	v_and_b32_e32 v121, 0xffff0000, v87
	v_add_f32_e32 v26, v26, v118
	v_add_f32_e32 v27, v27, v119
	v_add_f32_e32 v28, v28, v120
	v_add_f32_e32 v29, v29, v121
	v_lshlrev_b32_e32 v118, 16, v88
	v_and_b32_e32 v119, 0xffff0000, v88
	v_lshlrev_b32_e32 v120, 16, v89
	v_and_b32_e32 v121, 0xffff0000, v89
	v_add_f32_e32 v30, v30, v118
	v_add_f32_e32 v31, v31, v119
	v_add_f32_e32 v32, v32, v120
	v_add_f32_e32 v33, v33, v121
	v_mul_f32_e32 v114, v18, v18
	v_fmac_f32_e32 v114, v19, v19
	v_fmac_f32_e32 v114, v20, v20
	v_fmac_f32_e32 v114, v21, v21
	v_fmac_f32_e32 v114, v22, v22
	v_fmac_f32_e32 v114, v23, v23
	v_fmac_f32_e32 v114, v24, v24
	v_fmac_f32_e32 v114, v25, v25
	v_fmac_f32_e32 v114, v26, v26
	v_fmac_f32_e32 v114, v27, v27
	v_fmac_f32_e32 v114, v28, v28
	v_fmac_f32_e32 v114, v29, v29
	v_fmac_f32_e32 v114, v30, v30
	v_fmac_f32_e32 v114, v31, v31
	v_fmac_f32_e32 v114, v32, v32
	v_fmac_f32_e32 v114, v33, v33
	ds_bpermute_b32 v115, v142, v114
	s_waitcnt lgkmcnt(0)
	v_add_f32_e32 v114, v114, v115
	ds_bpermute_b32 v115, v143, v114
	s_waitcnt lgkmcnt(0)
	v_add_f32_e32 v114, v114, v115
	ds_bpermute_b32 v115, v144, v114
	s_waitcnt lgkmcnt(0)
	v_add_f32_e32 v114, v114, v115
	ds_bpermute_b32 v115, v145, v114
	s_waitcnt lgkmcnt(0)
	v_add_f32_e32 v114, v114, v115
	ds_bpermute_b32 v115, v146, v114
	s_waitcnt lgkmcnt(0)
	v_add_f32_e32 v114, v114, v115
	ds_bpermute_b32 v115, v147, v114
	s_waitcnt lgkmcnt(0)
	v_add_f32_e32 v114, v114, v115
	v_fmamk_f32 v114, v114, 0x3a800000, v124
	v_rsq_f32_e32 v116, v114
	s_nop 0
	v_mul_f32_e32 v118, v116, v196
	v_mul_f32_e32 v18, v18, v118
	v_mul_f32_e32 v119, v116, v197
	v_mul_f32_e32 v19, v19, v119
	v_mul_f32_e32 v120, v116, v198
	v_mul_f32_e32 v20, v20, v120
	v_mul_f32_e32 v121, v116, v199
	v_mul_f32_e32 v21, v21, v121
	global_store_dwordx4 v194, v[18:21], s[44:45] offset:0
	v_mul_f32_e32 v118, v116, v200
	v_mul_f32_e32 v22, v22, v118
	v_mul_f32_e32 v119, v116, v201
	v_mul_f32_e32 v23, v23, v119
	v_mul_f32_e32 v120, v116, v202
	v_mul_f32_e32 v24, v24, v120
	v_mul_f32_e32 v121, v116, v203
	v_mul_f32_e32 v25, v25, v121
	global_store_dwordx4 v194, v[22:25], s[44:45] offset:1024
	v_mul_f32_e32 v118, v116, v204
	v_mul_f32_e32 v26, v26, v118
	v_mul_f32_e32 v119, v116, v205
	v_mul_f32_e32 v27, v27, v119
	v_mul_f32_e32 v120, v116, v206
	v_mul_f32_e32 v28, v28, v120
	v_mul_f32_e32 v121, v116, v207
	v_mul_f32_e32 v29, v29, v121
	global_store_dwordx4 v194, v[26:29], s[44:45] offset:2048
	v_mul_f32_e32 v118, v116, v208
	v_mul_f32_e32 v30, v30, v118
	v_mul_f32_e32 v119, v116, v209
	v_mul_f32_e32 v31, v31, v119
	v_mul_f32_e32 v120, v116, v210
	v_mul_f32_e32 v32, v32, v120
	v_mul_f32_e32 v121, v116, v211
	v_mul_f32_e32 v33, v33, v121
	global_store_dwordx4 v194, v[30:33], s[44:45] offset:3072
	s_add_u32 s2, s52, 0x4000
	s_addc_u32 s3, s53, 0
	s_add_u32 s44, s56, 0x4000
	s_addc_u32 s45, s57, 0
	s_add_u32 s26, s54, 0x2000
	s_addc_u32 s27, s55, 0
	global_load_dwordx2 v[82:83], v188, s[26:27] offset:0 sc1
	global_load_dwordx2 v[84:85], v188, s[26:27] offset:512 sc1
	global_load_dwordx2 v[86:87], v188, s[26:27] offset:1024 sc1
	global_load_dwordx2 v[88:89], v188, s[26:27] offset:1536 sc1
	global_load_dwordx4 v[18:21], v194, s[2:3] offset:0 nt
	global_load_dwordx4 v[22:25], v194, s[2:3] offset:1024 nt
	global_load_dwordx4 v[26:29], v194, s[2:3] offset:2048 nt
	global_load_dwordx4 v[30:33], v194, s[2:3] offset:3072 nt
	s_waitcnt vmcnt(28)
	v_lshlrev_b32_e32 v118, 16, v90
	v_and_b32_e32 v119, 0xffff0000, v90
	v_lshlrev_b32_e32 v120, 16, v91
	v_and_b32_e32 v121, 0xffff0000, v91
	v_add_f32_e32 v34, v34, v118
	v_add_f32_e32 v35, v35, v119
	v_add_f32_e32 v36, v36, v120
	v_add_f32_e32 v37, v37, v121
	v_lshlrev_b32_e32 v118, 16, v92
	v_and_b32_e32 v119, 0xffff0000, v92
	v_lshlrev_b32_e32 v120, 16, v93
	v_and_b32_e32 v121, 0xffff0000, v93
	v_add_f32_e32 v38, v38, v118
	v_add_f32_e32 v39, v39, v119
	v_add_f32_e32 v40, v40, v120
	v_add_f32_e32 v41, v41, v121
	v_lshlrev_b32_e32 v118, 16, v94
	v_and_b32_e32 v119, 0xffff0000, v94
	v_lshlrev_b32_e32 v120, 16, v95
	v_and_b32_e32 v121, 0xffff0000, v95
	v_add_f32_e32 v42, v42, v118
	v_add_f32_e32 v43, v43, v119
	v_add_f32_e32 v44, v44, v120
	v_add_f32_e32 v45, v45, v121
	v_lshlrev_b32_e32 v118, 16, v96
	v_and_b32_e32 v119, 0xffff0000, v96
	v_lshlrev_b32_e32 v120, 16, v97
	v_and_b32_e32 v121, 0xffff0000, v97
	v_add_f32_e32 v46, v46, v118
	v_add_f32_e32 v47, v47, v119
	v_add_f32_e32 v48, v48, v120
	v_add_f32_e32 v49, v49, v121
	v_mul_f32_e32 v114, v34, v34
	v_fmac_f32_e32 v114, v35, v35
	v_fmac_f32_e32 v114, v36, v36
	v_fmac_f32_e32 v114, v37, v37
	v_fmac_f32_e32 v114, v38, v38
	v_fmac_f32_e32 v114, v39, v39
	v_fmac_f32_e32 v114, v40, v40
	v_fmac_f32_e32 v114, v41, v41
	v_fmac_f32_e32 v114, v42, v42
	v_fmac_f32_e32 v114, v43, v43
	v_fmac_f32_e32 v114, v44, v44
	v_fmac_f32_e32 v114, v45, v45
	v_fmac_f32_e32 v114, v46, v46
	v_fmac_f32_e32 v114, v47, v47
	v_fmac_f32_e32 v114, v48, v48
	v_fmac_f32_e32 v114, v49, v49
	ds_bpermute_b32 v115, v142, v114
	s_waitcnt lgkmcnt(0)
	v_add_f32_e32 v114, v114, v115
	ds_bpermute_b32 v115, v143, v114
	s_waitcnt lgkmcnt(0)
	v_add_f32_e32 v114, v114, v115
	ds_bpermute_b32 v115, v144, v114
	s_waitcnt lgkmcnt(0)
	v_add_f32_e32 v114, v114, v115
	ds_bpermute_b32 v115, v145, v114
	s_waitcnt lgkmcnt(0)
	v_add_f32_e32 v114, v114, v115
	ds_bpermute_b32 v115, v146, v114
	s_waitcnt lgkmcnt(0)
	v_add_f32_e32 v114, v114, v115
	ds_bpermute_b32 v115, v147, v114
	s_waitcnt lgkmcnt(0)
	v_add_f32_e32 v114, v114, v115
	v_fmamk_f32 v114, v114, 0x3a800000, v124
	v_rsq_f32_e32 v116, v114
	s_nop 0
	v_mul_f32_e32 v118, v116, v196
	v_mul_f32_e32 v34, v34, v118
	v_mul_f32_e32 v119, v116, v197
	v_mul_f32_e32 v35, v35, v119
	v_mul_f32_e32 v120, v116, v198
	v_mul_f32_e32 v36, v36, v120
	v_mul_f32_e32 v121, v116, v199
	v_mul_f32_e32 v37, v37, v121
	global_store_dwordx4 v194, v[34:37], s[46:47] offset:0
	v_mul_f32_e32 v118, v116, v200
	v_mul_f32_e32 v38, v38, v118
	v_mul_f32_e32 v119, v116, v201
	v_mul_f32_e32 v39, v39, v119
	v_mul_f32_e32 v120, v116, v202
	v_mul_f32_e32 v40, v40, v120
	v_mul_f32_e32 v121, v116, v203
	v_mul_f32_e32 v41, v41, v121
	global_store_dwordx4 v194, v[38:41], s[46:47] offset:1024
	v_mul_f32_e32 v118, v116, v204
	v_mul_f32_e32 v42, v42, v118
	v_mul_f32_e32 v119, v116, v205
	v_mul_f32_e32 v43, v43, v119
	v_mul_f32_e32 v120, v116, v206
	v_mul_f32_e32 v44, v44, v120
	v_mul_f32_e32 v121, v116, v207
	v_mul_f32_e32 v45, v45, v121
	global_store_dwordx4 v194, v[42:45], s[46:47] offset:2048
	v_mul_f32_e32 v118, v116, v208
	v_mul_f32_e32 v46, v46, v118
	v_mul_f32_e32 v119, v116, v209
	v_mul_f32_e32 v47, v47, v119
	v_mul_f32_e32 v120, v116, v210
	v_mul_f32_e32 v48, v48, v120
	v_mul_f32_e32 v121, v116, v211
	v_mul_f32_e32 v49, v49, v121
	global_store_dwordx4 v194, v[46:49], s[46:47] offset:3072
	s_add_u32 s4, s52, 0x5000
	s_addc_u32 s5, s53, 0
	s_add_u32 s46, s56, 0x5000
	s_addc_u32 s47, s57, 0
	s_add_u32 s28, s54, 0x2800
	s_addc_u32 s29, s55, 0
	global_load_dwordx2 v[90:91], v188, s[28:29] offset:0 sc1
	global_load_dwordx2 v[92:93], v188, s[28:29] offset:512 sc1
	global_load_dwordx2 v[94:95], v188, s[28:29] offset:1024 sc1
	global_load_dwordx2 v[96:97], v188, s[28:29] offset:1536 sc1
	global_load_dwordx4 v[34:37], v194, s[4:5] offset:0 nt
	global_load_dwordx4 v[38:41], v194, s[4:5] offset:1024 nt
	global_load_dwordx4 v[42:45], v194, s[4:5] offset:2048 nt
	global_load_dwordx4 v[46:49], v194, s[4:5] offset:3072 nt
	s_waitcnt vmcnt(32)
	v_lshlrev_b32_e32 v118, 16, v98
	v_and_b32_e32 v119, 0xffff0000, v98
	v_lshlrev_b32_e32 v120, 16, v99
	v_and_b32_e32 v121, 0xffff0000, v99
	v_add_f32_e32 v50, v50, v118
	v_add_f32_e32 v51, v51, v119
	v_add_f32_e32 v52, v52, v120
	v_add_f32_e32 v53, v53, v121
	v_lshlrev_b32_e32 v118, 16, v100
	v_and_b32_e32 v119, 0xffff0000, v100
	v_lshlrev_b32_e32 v120, 16, v101
	v_and_b32_e32 v121, 0xffff0000, v101
	v_add_f32_e32 v54, v54, v118
	v_add_f32_e32 v55, v55, v119
	v_add_f32_e32 v56, v56, v120
	v_add_f32_e32 v57, v57, v121
	v_lshlrev_b32_e32 v118, 16, v102
	v_and_b32_e32 v119, 0xffff0000, v102
	v_lshlrev_b32_e32 v120, 16, v103
	v_and_b32_e32 v121, 0xffff0000, v103
	v_add_f32_e32 v58, v58, v118
	v_add_f32_e32 v59, v59, v119
	v_add_f32_e32 v60, v60, v120
	v_add_f32_e32 v61, v61, v121
	v_lshlrev_b32_e32 v118, 16, v104
	v_and_b32_e32 v119, 0xffff0000, v104
	v_lshlrev_b32_e32 v120, 16, v105
	v_and_b32_e32 v121, 0xffff0000, v105
	v_add_f32_e32 v62, v62, v118
	v_add_f32_e32 v63, v63, v119
	v_add_f32_e32 v64, v64, v120
	v_add_f32_e32 v65, v65, v121
	v_mul_f32_e32 v114, v50, v50
	v_fmac_f32_e32 v114, v51, v51
	v_fmac_f32_e32 v114, v52, v52
	v_fmac_f32_e32 v114, v53, v53
	v_fmac_f32_e32 v114, v54, v54
	v_fmac_f32_e32 v114, v55, v55
	v_fmac_f32_e32 v114, v56, v56
	v_fmac_f32_e32 v114, v57, v57
	v_fmac_f32_e32 v114, v58, v58
	v_fmac_f32_e32 v114, v59, v59
	v_fmac_f32_e32 v114, v60, v60
	v_fmac_f32_e32 v114, v61, v61
	v_fmac_f32_e32 v114, v62, v62
	v_fmac_f32_e32 v114, v63, v63
	v_fmac_f32_e32 v114, v64, v64
	v_fmac_f32_e32 v114, v65, v65
	ds_bpermute_b32 v115, v142, v114
	s_waitcnt lgkmcnt(0)
	v_add_f32_e32 v114, v114, v115
	ds_bpermute_b32 v115, v143, v114
	s_waitcnt lgkmcnt(0)
	v_add_f32_e32 v114, v114, v115
	ds_bpermute_b32 v115, v144, v114
	s_waitcnt lgkmcnt(0)
	v_add_f32_e32 v114, v114, v115
	ds_bpermute_b32 v115, v145, v114
	s_waitcnt lgkmcnt(0)
	v_add_f32_e32 v114, v114, v115
	ds_bpermute_b32 v115, v146, v114
	s_waitcnt lgkmcnt(0)
	v_add_f32_e32 v114, v114, v115
	ds_bpermute_b32 v115, v147, v114
	s_waitcnt lgkmcnt(0)
	v_add_f32_e32 v114, v114, v115
	v_fmamk_f32 v114, v114, 0x3a800000, v124
	v_rsq_f32_e32 v116, v114
	s_nop 0
	v_mul_f32_e32 v118, v116, v196
	v_mul_f32_e32 v50, v50, v118
	v_mul_f32_e32 v119, v116, v197
	v_mul_f32_e32 v51, v51, v119
	v_mul_f32_e32 v120, v116, v198
	v_mul_f32_e32 v52, v52, v120
	v_mul_f32_e32 v121, v116, v199
	v_mul_f32_e32 v53, v53, v121
	global_store_dwordx4 v194, v[50:53], s[48:49] offset:0
	v_mul_f32_e32 v118, v116, v200
	v_mul_f32_e32 v54, v54, v118
	v_mul_f32_e32 v119, v116, v201
	v_mul_f32_e32 v55, v55, v119
	v_mul_f32_e32 v120, v116, v202
	v_mul_f32_e32 v56, v56, v120
	v_mul_f32_e32 v121, v116, v203
	v_mul_f32_e32 v57, v57, v121
	global_store_dwordx4 v194, v[54:57], s[48:49] offset:1024
	v_mul_f32_e32 v118, v116, v204
	v_mul_f32_e32 v58, v58, v118
	v_mul_f32_e32 v119, v116, v205
	v_mul_f32_e32 v59, v59, v119
	v_mul_f32_e32 v120, v116, v206
	v_mul_f32_e32 v60, v60, v120
	v_mul_f32_e32 v121, v116, v207
	v_mul_f32_e32 v61, v61, v121
	global_store_dwordx4 v194, v[58:61], s[48:49] offset:2048
	v_mul_f32_e32 v118, v116, v208
	v_mul_f32_e32 v62, v62, v118
	v_mul_f32_e32 v119, v116, v209
	v_mul_f32_e32 v63, v63, v119
	v_mul_f32_e32 v120, v116, v210
	v_mul_f32_e32 v64, v64, v120
	v_mul_f32_e32 v121, v116, v211
	v_mul_f32_e32 v65, v65, v121
	global_store_dwordx4 v194, v[62:65], s[48:49] offset:3072
	s_add_u32 s6, s52, 0x6000
	s_addc_u32 s7, s53, 0
	s_add_u32 s48, s56, 0x6000
	s_addc_u32 s49, s57, 0
	s_add_u32 s30, s54, 0x3000
	s_addc_u32 s31, s55, 0
	global_load_dwordx2 v[98:99], v188, s[30:31] offset:0 sc1
	global_load_dwordx2 v[100:101], v188, s[30:31] offset:512 sc1
	global_load_dwordx2 v[102:103], v188, s[30:31] offset:1024 sc1
	global_load_dwordx2 v[104:105], v188, s[30:31] offset:1536 sc1
	global_load_dwordx4 v[50:53], v194, s[6:7] offset:0 nt
	global_load_dwordx4 v[54:57], v194, s[6:7] offset:1024 nt
	global_load_dwordx4 v[58:61], v194, s[6:7] offset:2048 nt
	global_load_dwordx4 v[62:65], v194, s[6:7] offset:3072 nt
	s_waitcnt vmcnt(36)
	v_lshlrev_b32_e32 v118, 16, v106
	v_and_b32_e32 v119, 0xffff0000, v106
	v_lshlrev_b32_e32 v120, 16, v107
	v_and_b32_e32 v121, 0xffff0000, v107
	v_add_f32_e32 v66, v66, v118
	v_add_f32_e32 v67, v67, v119
	v_add_f32_e32 v68, v68, v120
	v_add_f32_e32 v69, v69, v121
	v_lshlrev_b32_e32 v118, 16, v108
	v_and_b32_e32 v119, 0xffff0000, v108
	v_lshlrev_b32_e32 v120, 16, v109
	v_and_b32_e32 v121, 0xffff0000, v109
	v_add_f32_e32 v70, v70, v118
	v_add_f32_e32 v71, v71, v119
	v_add_f32_e32 v72, v72, v120
	v_add_f32_e32 v73, v73, v121
	v_lshlrev_b32_e32 v118, 16, v110
	v_and_b32_e32 v119, 0xffff0000, v110
	v_lshlrev_b32_e32 v120, 16, v111
	v_and_b32_e32 v121, 0xffff0000, v111
	v_add_f32_e32 v74, v74, v118
	v_add_f32_e32 v75, v75, v119
	v_add_f32_e32 v76, v76, v120
	v_add_f32_e32 v77, v77, v121
	v_lshlrev_b32_e32 v118, 16, v112
	v_and_b32_e32 v119, 0xffff0000, v112
	v_lshlrev_b32_e32 v120, 16, v113
	v_and_b32_e32 v121, 0xffff0000, v113
	v_add_f32_e32 v78, v78, v118
	v_add_f32_e32 v79, v79, v119
	v_add_f32_e32 v80, v80, v120
	v_add_f32_e32 v81, v81, v121
	v_mul_f32_e32 v114, v66, v66
	v_fmac_f32_e32 v114, v67, v67
	v_fmac_f32_e32 v114, v68, v68
	v_fmac_f32_e32 v114, v69, v69
	v_fmac_f32_e32 v114, v70, v70
	v_fmac_f32_e32 v114, v71, v71
	v_fmac_f32_e32 v114, v72, v72
	v_fmac_f32_e32 v114, v73, v73
	v_fmac_f32_e32 v114, v74, v74
	v_fmac_f32_e32 v114, v75, v75
	v_fmac_f32_e32 v114, v76, v76
	v_fmac_f32_e32 v114, v77, v77
	v_fmac_f32_e32 v114, v78, v78
	v_fmac_f32_e32 v114, v79, v79
	v_fmac_f32_e32 v114, v80, v80
	v_fmac_f32_e32 v114, v81, v81
	ds_bpermute_b32 v115, v142, v114
	s_waitcnt lgkmcnt(0)
	v_add_f32_e32 v114, v114, v115
	ds_bpermute_b32 v115, v143, v114
	s_waitcnt lgkmcnt(0)
	v_add_f32_e32 v114, v114, v115
	ds_bpermute_b32 v115, v144, v114
	s_waitcnt lgkmcnt(0)
	v_add_f32_e32 v114, v114, v115
	ds_bpermute_b32 v115, v145, v114
	s_waitcnt lgkmcnt(0)
	v_add_f32_e32 v114, v114, v115
	ds_bpermute_b32 v115, v146, v114
	s_waitcnt lgkmcnt(0)
	v_add_f32_e32 v114, v114, v115
	ds_bpermute_b32 v115, v147, v114
	s_waitcnt lgkmcnt(0)
	v_add_f32_e32 v114, v114, v115
	v_fmamk_f32 v114, v114, 0x3a800000, v124
	v_rsq_f32_e32 v116, v114
	s_nop 0
	v_mul_f32_e32 v118, v116, v196
	v_mul_f32_e32 v66, v66, v118
	v_mul_f32_e32 v119, v116, v197
	v_mul_f32_e32 v67, v67, v119
	v_mul_f32_e32 v120, v116, v198
	v_mul_f32_e32 v68, v68, v120
	v_mul_f32_e32 v121, v116, v199
	v_mul_f32_e32 v69, v69, v121
	global_store_dwordx4 v194, v[66:69], s[50:51] offset:0
	v_mul_f32_e32 v118, v116, v200
	v_mul_f32_e32 v70, v70, v118
	v_mul_f32_e32 v119, v116, v201
	v_mul_f32_e32 v71, v71, v119
	v_mul_f32_e32 v120, v116, v202
	v_mul_f32_e32 v72, v72, v120
	v_mul_f32_e32 v121, v116, v203
	v_mul_f32_e32 v73, v73, v121
	global_store_dwordx4 v194, v[70:73], s[50:51] offset:1024
	v_mul_f32_e32 v118, v116, v204
	v_mul_f32_e32 v74, v74, v118
	v_mul_f32_e32 v119, v116, v205
	v_mul_f32_e32 v75, v75, v119
	v_mul_f32_e32 v120, v116, v206
	v_mul_f32_e32 v76, v76, v120
	v_mul_f32_e32 v121, v116, v207
	v_mul_f32_e32 v77, v77, v121
	global_store_dwordx4 v194, v[74:77], s[50:51] offset:2048
	v_mul_f32_e32 v118, v116, v208
	v_mul_f32_e32 v78, v78, v118
	v_mul_f32_e32 v119, v116, v209
	v_mul_f32_e32 v79, v79, v119
	v_mul_f32_e32 v120, v116, v210
	v_mul_f32_e32 v80, v80, v120
	v_mul_f32_e32 v121, v116, v211
	v_mul_f32_e32 v81, v81, v121
	global_store_dwordx4 v194, v[78:81], s[50:51] offset:3072
	s_add_u32 s8, s52, 0x7000
	s_addc_u32 s9, s53, 0
	s_add_u32 s50, s56, 0x7000
	s_addc_u32 s51, s57, 0
	s_add_u32 s34, s54, 0x3800
	s_addc_u32 s35, s55, 0
	global_load_dwordx2 v[106:107], v188, s[34:35] offset:0 sc1
	global_load_dwordx2 v[108:109], v188, s[34:35] offset:512 sc1
	global_load_dwordx2 v[110:111], v188, s[34:35] offset:1024 sc1
	global_load_dwordx2 v[112:113], v188, s[34:35] offset:1536 sc1
	global_load_dwordx4 v[66:69], v194, s[8:9] offset:0 nt
	global_load_dwordx4 v[70:73], v194, s[8:9] offset:1024 nt
	global_load_dwordx4 v[74:77], v194, s[8:9] offset:2048 nt
	global_load_dwordx4 v[78:81], v194, s[8:9] offset:3072 nt
	s_waitcnt vmcnt(36)
	v_lshlrev_b32_e32 v118, 16, v82
	v_and_b32_e32 v119, 0xffff0000, v82
	v_lshlrev_b32_e32 v120, 16, v83
	v_and_b32_e32 v121, 0xffff0000, v83
	v_add_f32_e32 v18, v18, v118
	v_add_f32_e32 v19, v19, v119
	v_add_f32_e32 v20, v20, v120
	v_add_f32_e32 v21, v21, v121
	v_lshlrev_b32_e32 v118, 16, v84
	v_and_b32_e32 v119, 0xffff0000, v84
	v_lshlrev_b32_e32 v120, 16, v85
	v_and_b32_e32 v121, 0xffff0000, v85
	v_add_f32_e32 v22, v22, v118
	v_add_f32_e32 v23, v23, v119
	v_add_f32_e32 v24, v24, v120
	v_add_f32_e32 v25, v25, v121
	v_lshlrev_b32_e32 v118, 16, v86
	v_and_b32_e32 v119, 0xffff0000, v86
	v_lshlrev_b32_e32 v120, 16, v87
	v_and_b32_e32 v121, 0xffff0000, v87
	v_add_f32_e32 v26, v26, v118
	v_add_f32_e32 v27, v27, v119
	v_add_f32_e32 v28, v28, v120
	v_add_f32_e32 v29, v29, v121
	v_lshlrev_b32_e32 v118, 16, v88
	v_and_b32_e32 v119, 0xffff0000, v88
	v_lshlrev_b32_e32 v120, 16, v89
	v_and_b32_e32 v121, 0xffff0000, v89
	v_add_f32_e32 v30, v30, v118
	v_add_f32_e32 v31, v31, v119
	v_add_f32_e32 v32, v32, v120
	v_add_f32_e32 v33, v33, v121
	v_mul_f32_e32 v114, v18, v18
	v_fmac_f32_e32 v114, v19, v19
	v_fmac_f32_e32 v114, v20, v20
	v_fmac_f32_e32 v114, v21, v21
	v_fmac_f32_e32 v114, v22, v22
	v_fmac_f32_e32 v114, v23, v23
	v_fmac_f32_e32 v114, v24, v24
	v_fmac_f32_e32 v114, v25, v25
	v_fmac_f32_e32 v114, v26, v26
	v_fmac_f32_e32 v114, v27, v27
	v_fmac_f32_e32 v114, v28, v28
	v_fmac_f32_e32 v114, v29, v29
	v_fmac_f32_e32 v114, v30, v30
	v_fmac_f32_e32 v114, v31, v31
	v_fmac_f32_e32 v114, v32, v32
	v_fmac_f32_e32 v114, v33, v33
	ds_bpermute_b32 v115, v142, v114
	s_waitcnt lgkmcnt(0)
	v_add_f32_e32 v114, v114, v115
	ds_bpermute_b32 v115, v143, v114
	s_waitcnt lgkmcnt(0)
	v_add_f32_e32 v114, v114, v115
	ds_bpermute_b32 v115, v144, v114
	s_waitcnt lgkmcnt(0)
	v_add_f32_e32 v114, v114, v115
	ds_bpermute_b32 v115, v145, v114
	s_waitcnt lgkmcnt(0)
	v_add_f32_e32 v114, v114, v115
	ds_bpermute_b32 v115, v146, v114
	s_waitcnt lgkmcnt(0)
	v_add_f32_e32 v114, v114, v115
	ds_bpermute_b32 v115, v147, v114
	s_waitcnt lgkmcnt(0)
	v_add_f32_e32 v114, v114, v115
	v_fmamk_f32 v114, v114, 0x3a800000, v124
	v_rsq_f32_e32 v116, v114
	s_nop 0
	v_mul_f32_e32 v118, v116, v196
	v_mul_f32_e32 v18, v18, v118
	v_mul_f32_e32 v119, v116, v197
	v_mul_f32_e32 v19, v19, v119
	v_mul_f32_e32 v120, v116, v198
	v_mul_f32_e32 v20, v20, v120
	v_mul_f32_e32 v121, v116, v199
	v_mul_f32_e32 v21, v21, v121
	global_store_dwordx4 v194, v[18:21], s[44:45] offset:0
	v_mul_f32_e32 v118, v116, v200
	v_mul_f32_e32 v22, v22, v118
	v_mul_f32_e32 v119, v116, v201
	v_mul_f32_e32 v23, v23, v119
	v_mul_f32_e32 v120, v116, v202
	v_mul_f32_e32 v24, v24, v120
	v_mul_f32_e32 v121, v116, v203
	v_mul_f32_e32 v25, v25, v121
	global_store_dwordx4 v194, v[22:25], s[44:45] offset:1024
	v_mul_f32_e32 v118, v116, v204
	v_mul_f32_e32 v26, v26, v118
	v_mul_f32_e32 v119, v116, v205
	v_mul_f32_e32 v27, v27, v119
	v_mul_f32_e32 v120, v116, v206
	v_mul_f32_e32 v28, v28, v120
	v_mul_f32_e32 v121, v116, v207
	v_mul_f32_e32 v29, v29, v121
	global_store_dwordx4 v194, v[26:29], s[44:45] offset:2048
	v_mul_f32_e32 v118, v116, v208
	v_mul_f32_e32 v30, v30, v118
	v_mul_f32_e32 v119, v116, v209
	v_mul_f32_e32 v31, v31, v119
	v_mul_f32_e32 v120, v116, v210
	v_mul_f32_e32 v32, v32, v120
	v_mul_f32_e32 v121, v116, v211
	v_mul_f32_e32 v33, v33, v121
	global_store_dwordx4 v194, v[30:33], s[44:45] offset:3072
	s_waitcnt vmcnt(28)
	v_lshlrev_b32_e32 v118, 16, v90
	v_and_b32_e32 v119, 0xffff0000, v90
	v_lshlrev_b32_e32 v120, 16, v91
	v_and_b32_e32 v121, 0xffff0000, v91
	v_add_f32_e32 v34, v34, v118
	v_add_f32_e32 v35, v35, v119
	v_add_f32_e32 v36, v36, v120
	v_add_f32_e32 v37, v37, v121
	v_lshlrev_b32_e32 v118, 16, v92
	v_and_b32_e32 v119, 0xffff0000, v92
	v_lshlrev_b32_e32 v120, 16, v93
	v_and_b32_e32 v121, 0xffff0000, v93
	v_add_f32_e32 v38, v38, v118
	v_add_f32_e32 v39, v39, v119
	v_add_f32_e32 v40, v40, v120
	v_add_f32_e32 v41, v41, v121
	v_lshlrev_b32_e32 v118, 16, v94
	v_and_b32_e32 v119, 0xffff0000, v94
	v_lshlrev_b32_e32 v120, 16, v95
	v_and_b32_e32 v121, 0xffff0000, v95
	v_add_f32_e32 v42, v42, v118
	v_add_f32_e32 v43, v43, v119
	v_add_f32_e32 v44, v44, v120
	v_add_f32_e32 v45, v45, v121
	v_lshlrev_b32_e32 v118, 16, v96
	v_and_b32_e32 v119, 0xffff0000, v96
	v_lshlrev_b32_e32 v120, 16, v97
	v_and_b32_e32 v121, 0xffff0000, v97
	v_add_f32_e32 v46, v46, v118
	v_add_f32_e32 v47, v47, v119
	v_add_f32_e32 v48, v48, v120
	v_add_f32_e32 v49, v49, v121
	v_mul_f32_e32 v114, v34, v34
	v_fmac_f32_e32 v114, v35, v35
	v_fmac_f32_e32 v114, v36, v36
	v_fmac_f32_e32 v114, v37, v37
	v_fmac_f32_e32 v114, v38, v38
	v_fmac_f32_e32 v114, v39, v39
	v_fmac_f32_e32 v114, v40, v40
	v_fmac_f32_e32 v114, v41, v41
	v_fmac_f32_e32 v114, v42, v42
	v_fmac_f32_e32 v114, v43, v43
	v_fmac_f32_e32 v114, v44, v44
	v_fmac_f32_e32 v114, v45, v45
	v_fmac_f32_e32 v114, v46, v46
	v_fmac_f32_e32 v114, v47, v47
	v_fmac_f32_e32 v114, v48, v48
	v_fmac_f32_e32 v114, v49, v49
	ds_bpermute_b32 v115, v142, v114
	s_waitcnt lgkmcnt(0)
	v_add_f32_e32 v114, v114, v115
	ds_bpermute_b32 v115, v143, v114
	s_waitcnt lgkmcnt(0)
	v_add_f32_e32 v114, v114, v115
	ds_bpermute_b32 v115, v144, v114
	s_waitcnt lgkmcnt(0)
	v_add_f32_e32 v114, v114, v115
	ds_bpermute_b32 v115, v145, v114
	s_waitcnt lgkmcnt(0)
	v_add_f32_e32 v114, v114, v115
	ds_bpermute_b32 v115, v146, v114
	s_waitcnt lgkmcnt(0)
	v_add_f32_e32 v114, v114, v115
	ds_bpermute_b32 v115, v147, v114
	s_waitcnt lgkmcnt(0)
	v_add_f32_e32 v114, v114, v115
	v_fmamk_f32 v114, v114, 0x3a800000, v124
	v_rsq_f32_e32 v116, v114
	s_nop 0
	v_mul_f32_e32 v118, v116, v196
	v_mul_f32_e32 v34, v34, v118
	v_mul_f32_e32 v119, v116, v197
	v_mul_f32_e32 v35, v35, v119
	v_mul_f32_e32 v120, v116, v198
	v_mul_f32_e32 v36, v36, v120
	v_mul_f32_e32 v121, v116, v199
	v_mul_f32_e32 v37, v37, v121
	global_store_dwordx4 v194, v[34:37], s[46:47] offset:0
	v_mul_f32_e32 v118, v116, v200
	v_mul_f32_e32 v38, v38, v118
	v_mul_f32_e32 v119, v116, v201
	v_mul_f32_e32 v39, v39, v119
	v_mul_f32_e32 v120, v116, v202
	v_mul_f32_e32 v40, v40, v120
	v_mul_f32_e32 v121, v116, v203
	v_mul_f32_e32 v41, v41, v121
	global_store_dwordx4 v194, v[38:41], s[46:47] offset:1024
	v_mul_f32_e32 v118, v116, v204
	v_mul_f32_e32 v42, v42, v118
	v_mul_f32_e32 v119, v116, v205
	v_mul_f32_e32 v43, v43, v119
	v_mul_f32_e32 v120, v116, v206
	v_mul_f32_e32 v44, v44, v120
	v_mul_f32_e32 v121, v116, v207
	v_mul_f32_e32 v45, v45, v121
	global_store_dwordx4 v194, v[42:45], s[46:47] offset:2048
	v_mul_f32_e32 v118, v116, v208
	v_mul_f32_e32 v46, v46, v118
	v_mul_f32_e32 v119, v116, v209
	v_mul_f32_e32 v47, v47, v119
	v_mul_f32_e32 v120, v116, v210
	v_mul_f32_e32 v48, v48, v120
	v_mul_f32_e32 v121, v116, v211
	v_mul_f32_e32 v49, v49, v121
	global_store_dwordx4 v194, v[46:49], s[46:47] offset:3072
	s_waitcnt vmcnt(20)
	v_lshlrev_b32_e32 v118, 16, v98
	v_and_b32_e32 v119, 0xffff0000, v98
	v_lshlrev_b32_e32 v120, 16, v99
	v_and_b32_e32 v121, 0xffff0000, v99
	v_add_f32_e32 v50, v50, v118
	v_add_f32_e32 v51, v51, v119
	v_add_f32_e32 v52, v52, v120
	v_add_f32_e32 v53, v53, v121
	v_lshlrev_b32_e32 v118, 16, v100
	v_and_b32_e32 v119, 0xffff0000, v100
	v_lshlrev_b32_e32 v120, 16, v101
	v_and_b32_e32 v121, 0xffff0000, v101
	v_add_f32_e32 v54, v54, v118
	v_add_f32_e32 v55, v55, v119
	v_add_f32_e32 v56, v56, v120
	v_add_f32_e32 v57, v57, v121
	v_lshlrev_b32_e32 v118, 16, v102
	v_and_b32_e32 v119, 0xffff0000, v102
	v_lshlrev_b32_e32 v120, 16, v103
	v_and_b32_e32 v121, 0xffff0000, v103
	v_add_f32_e32 v58, v58, v118
	v_add_f32_e32 v59, v59, v119
	v_add_f32_e32 v60, v60, v120
	v_add_f32_e32 v61, v61, v121
	v_lshlrev_b32_e32 v118, 16, v104
	v_and_b32_e32 v119, 0xffff0000, v104
	v_lshlrev_b32_e32 v120, 16, v105
	v_and_b32_e32 v121, 0xffff0000, v105
	v_add_f32_e32 v62, v62, v118
	v_add_f32_e32 v63, v63, v119
	v_add_f32_e32 v64, v64, v120
	v_add_f32_e32 v65, v65, v121
	v_mul_f32_e32 v114, v50, v50
	v_fmac_f32_e32 v114, v51, v51
	v_fmac_f32_e32 v114, v52, v52
	v_fmac_f32_e32 v114, v53, v53
	v_fmac_f32_e32 v114, v54, v54
	v_fmac_f32_e32 v114, v55, v55
	v_fmac_f32_e32 v114, v56, v56
	v_fmac_f32_e32 v114, v57, v57
	v_fmac_f32_e32 v114, v58, v58
	v_fmac_f32_e32 v114, v59, v59
	v_fmac_f32_e32 v114, v60, v60
	v_fmac_f32_e32 v114, v61, v61
	v_fmac_f32_e32 v114, v62, v62
	v_fmac_f32_e32 v114, v63, v63
	v_fmac_f32_e32 v114, v64, v64
	v_fmac_f32_e32 v114, v65, v65
	ds_bpermute_b32 v115, v142, v114
	s_waitcnt lgkmcnt(0)
	v_add_f32_e32 v114, v114, v115
	ds_bpermute_b32 v115, v143, v114
	s_waitcnt lgkmcnt(0)
	v_add_f32_e32 v114, v114, v115
	ds_bpermute_b32 v115, v144, v114
	s_waitcnt lgkmcnt(0)
	v_add_f32_e32 v114, v114, v115
	ds_bpermute_b32 v115, v145, v114
	s_waitcnt lgkmcnt(0)
	v_add_f32_e32 v114, v114, v115
	ds_bpermute_b32 v115, v146, v114
	s_waitcnt lgkmcnt(0)
	v_add_f32_e32 v114, v114, v115
	ds_bpermute_b32 v115, v147, v114
	s_waitcnt lgkmcnt(0)
	v_add_f32_e32 v114, v114, v115
	v_fmamk_f32 v114, v114, 0x3a800000, v124
	v_rsq_f32_e32 v116, v114
	s_nop 0
	v_mul_f32_e32 v118, v116, v196
	v_mul_f32_e32 v50, v50, v118
	v_mul_f32_e32 v119, v116, v197
	v_mul_f32_e32 v51, v51, v119
	v_mul_f32_e32 v120, v116, v198
	v_mul_f32_e32 v52, v52, v120
	v_mul_f32_e32 v121, v116, v199
	v_mul_f32_e32 v53, v53, v121
	global_store_dwordx4 v194, v[50:53], s[48:49] offset:0
	v_mul_f32_e32 v118, v116, v200
	v_mul_f32_e32 v54, v54, v118
	v_mul_f32_e32 v119, v116, v201
	v_mul_f32_e32 v55, v55, v119
	v_mul_f32_e32 v120, v116, v202
	v_mul_f32_e32 v56, v56, v120
	v_mul_f32_e32 v121, v116, v203
	v_mul_f32_e32 v57, v57, v121
	global_store_dwordx4 v194, v[54:57], s[48:49] offset:1024
	v_mul_f32_e32 v118, v116, v204
	v_mul_f32_e32 v58, v58, v118
	v_mul_f32_e32 v119, v116, v205
	v_mul_f32_e32 v59, v59, v119
	v_mul_f32_e32 v120, v116, v206
	v_mul_f32_e32 v60, v60, v120
	v_mul_f32_e32 v121, v116, v207
	v_mul_f32_e32 v61, v61, v121
	global_store_dwordx4 v194, v[58:61], s[48:49] offset:2048
	v_mul_f32_e32 v118, v116, v208
	v_mul_f32_e32 v62, v62, v118
	v_mul_f32_e32 v119, v116, v209
	v_mul_f32_e32 v63, v63, v119
	v_mul_f32_e32 v120, v116, v210
	v_mul_f32_e32 v64, v64, v120
	v_mul_f32_e32 v121, v116, v211
	v_mul_f32_e32 v65, v65, v121
	global_store_dwordx4 v194, v[62:65], s[48:49] offset:3072
	s_waitcnt vmcnt(12)
	v_lshlrev_b32_e32 v118, 16, v106
	v_and_b32_e32 v119, 0xffff0000, v106
	v_lshlrev_b32_e32 v120, 16, v107
	v_and_b32_e32 v121, 0xffff0000, v107
	v_add_f32_e32 v66, v66, v118
	v_add_f32_e32 v67, v67, v119
	v_add_f32_e32 v68, v68, v120
	v_add_f32_e32 v69, v69, v121
	v_lshlrev_b32_e32 v118, 16, v108
	v_and_b32_e32 v119, 0xffff0000, v108
	v_lshlrev_b32_e32 v120, 16, v109
	v_and_b32_e32 v121, 0xffff0000, v109
	v_add_f32_e32 v70, v70, v118
	v_add_f32_e32 v71, v71, v119
	v_add_f32_e32 v72, v72, v120
	v_add_f32_e32 v73, v73, v121
	v_lshlrev_b32_e32 v118, 16, v110
	v_and_b32_e32 v119, 0xffff0000, v110
	v_lshlrev_b32_e32 v120, 16, v111
	v_and_b32_e32 v121, 0xffff0000, v111
	v_add_f32_e32 v74, v74, v118
	v_add_f32_e32 v75, v75, v119
	v_add_f32_e32 v76, v76, v120
	v_add_f32_e32 v77, v77, v121
	v_lshlrev_b32_e32 v118, 16, v112
	v_and_b32_e32 v119, 0xffff0000, v112
	v_lshlrev_b32_e32 v120, 16, v113
	v_and_b32_e32 v121, 0xffff0000, v113
	v_add_f32_e32 v78, v78, v118
	v_add_f32_e32 v79, v79, v119
	v_add_f32_e32 v80, v80, v120
	v_add_f32_e32 v81, v81, v121
	v_mul_f32_e32 v114, v66, v66
	v_fmac_f32_e32 v114, v67, v67
	v_fmac_f32_e32 v114, v68, v68
	v_fmac_f32_e32 v114, v69, v69
	v_fmac_f32_e32 v114, v70, v70
	v_fmac_f32_e32 v114, v71, v71
	v_fmac_f32_e32 v114, v72, v72
	v_fmac_f32_e32 v114, v73, v73
	v_fmac_f32_e32 v114, v74, v74
	v_fmac_f32_e32 v114, v75, v75
	v_fmac_f32_e32 v114, v76, v76
	v_fmac_f32_e32 v114, v77, v77
	v_fmac_f32_e32 v114, v78, v78
	v_fmac_f32_e32 v114, v79, v79
	v_fmac_f32_e32 v114, v80, v80
	v_fmac_f32_e32 v114, v81, v81
	ds_bpermute_b32 v115, v142, v114
	s_waitcnt lgkmcnt(0)
	v_add_f32_e32 v114, v114, v115
	ds_bpermute_b32 v115, v143, v114
	s_waitcnt lgkmcnt(0)
	v_add_f32_e32 v114, v114, v115
	ds_bpermute_b32 v115, v144, v114
	s_waitcnt lgkmcnt(0)
	v_add_f32_e32 v114, v114, v115
	ds_bpermute_b32 v115, v145, v114
	s_waitcnt lgkmcnt(0)
	v_add_f32_e32 v114, v114, v115
	ds_bpermute_b32 v115, v146, v114
	s_waitcnt lgkmcnt(0)
	v_add_f32_e32 v114, v114, v115
	ds_bpermute_b32 v115, v147, v114
	s_waitcnt lgkmcnt(0)
	v_add_f32_e32 v114, v114, v115
	v_fmamk_f32 v114, v114, 0x3a800000, v124
	v_rsq_f32_e32 v116, v114
	s_nop 0
	v_mul_f32_e32 v118, v116, v196
	v_mul_f32_e32 v66, v66, v118
	v_mul_f32_e32 v119, v116, v197
	v_mul_f32_e32 v67, v67, v119
	v_mul_f32_e32 v120, v116, v198
	v_mul_f32_e32 v68, v68, v120
	v_mul_f32_e32 v121, v116, v199
	v_mul_f32_e32 v69, v69, v121
	global_store_dwordx4 v194, v[66:69], s[50:51] offset:0
	v_mul_f32_e32 v118, v116, v200
	v_mul_f32_e32 v70, v70, v118
	v_mul_f32_e32 v119, v116, v201
	v_mul_f32_e32 v71, v71, v119
	v_mul_f32_e32 v120, v116, v202
	v_mul_f32_e32 v72, v72, v120
	v_mul_f32_e32 v121, v116, v203
	v_mul_f32_e32 v73, v73, v121
	global_store_dwordx4 v194, v[70:73], s[50:51] offset:1024
	v_mul_f32_e32 v118, v116, v204
	v_mul_f32_e32 v74, v74, v118
	v_mul_f32_e32 v119, v116, v205
	v_mul_f32_e32 v75, v75, v119
	v_mul_f32_e32 v120, v116, v206
	v_mul_f32_e32 v76, v76, v120
	v_mul_f32_e32 v121, v116, v207
	v_mul_f32_e32 v77, v77, v121
	global_store_dwordx4 v194, v[74:77], s[50:51] offset:2048
	v_mul_f32_e32 v118, v116, v208
	v_mul_f32_e32 v78, v78, v118
	v_mul_f32_e32 v119, v116, v209
	v_mul_f32_e32 v79, v79, v119
	v_mul_f32_e32 v120, v116, v210
	v_mul_f32_e32 v80, v80, v120
	v_mul_f32_e32 v121, v116, v211
	v_mul_f32_e32 v81, v81, v121
	global_store_dwordx4 v194, v[78:81], s[50:51] offset:3072
	s_add_i32 s83, s83, 1
	s_branch .Lp45_loop
.Lp45_skip:
	v_readlane_b32 s68, v254, 9
	s_add_i32 s75, s75, s68
	s_add_i32 s33, s33, s68
	v_readlane_b32 s70, v254, 7
	v_readlane_b32 s69, v254, 10
	s_cmpk_gt_i32 s75, 0x2ff
	v_readlane_b32 s71, v254, 8
	s_barrier
	s_cbranch_scc0 .LBB0_374

.LBB0_429:
	s_or_b64 exec, exec, s[0:1]
	v_readlane_b32 s0, v254, 3
	v_readlane_b32 s1, v254, 4
	s_andn2_b64 vcc, exec, s[0:1]
	s_waitcnt lgkmcnt(0)
	s_barrier
	s_cbranch_vccnz .LBB0_434
	s_cmp_lg_u32 s78, 0
	s_cbranch_scc1 .LBB0_434
	v_mov_b32_e32 v195, 0
	v_readlane_b32 s0, v254, 22
	v_mov_b32_e32 v189, v195
	v_readlane_b32 s1, v254, 23
	s_ashr_i32 s11, s10, 31
	s_ashr_i32 s57, s56, 31
	v_lshl_add_u64 v[2:3], s[0:1], 0, v[188:189]
	s_lshl_b64 s[0:1], s[10:11], 12
	s_add_u32 s0, s12, s0
	v_lshl_add_u64 v[0:1], s[38:39], 0, v[194:195]
	v_lshl_add_u64 v[4:5], s[40:41], 0, v[194:195]
	s_addc_u32 s1, s13, s1
	s_lshl_b64 s[2:3], s[56:57], 12
	s_mov_b32 s5, 0
	v_mov_b32_e32 v6, 0x358637bd
	s_mov_b32 s12, 0x800000
	s_branch .LBB0_432
